# adds: MoBA prep q/k stores staged through per-wave LDS scratch and written wave-contiguous (full lines)
# speedup vs baseline: 1.0140x; 1.0127x over previous
; __device__ __forceinline__ void moba_prep_load(const Args& a, int tid, int u, PrepIn& r) {
;     const int b = u >> 6, j = (u >> 3) & 7, h = u & 7, tok = tid >> 1, half = tid & 1;
;     const size_t row = (size_t)b * SEQ + j * 256 + tok;
;     const bf16_t* p = (const bf16_t*)(a.ws + WS_PROJ) + row * NCOL + h * 64 + half * 32;
;     const bf16_t* pk = (const bf16_t*)(a.ws + WS_KC) + ((size_t)(b * 8 + h) * SEQ + j * 256 + tok) * 64 + half * 32;
; #pragma unroll
;     for (int c = 0; c < 4; ++c) { r.q[c] = *(const u32x4*)(p + CQA + c * 8); r.k[c] = *(const u32x4*)(pk + c * 8); }
;     const f32x4* rope = (const f32x4*)((const float*)(a.ws + WS_ROPE) + row * 16);
;     const f32x4 c0 = rope[0], c1 = rope[1], s0 = rope[2], s1 = rope[3];
;     r.cs[0] = c0.x; r.cs[1] = c0.y; r.cs[2] = c0.z; r.cs[3] = c0.w; r.cs[4] = c1.x; r.cs[5] = c1.y; r.cs[6] = c1.z; r.cs[7] = c1.w;
;     r.sn[0] = s0.x; r.sn[1] = s0.y; r.sn[2] = s0.z; r.sn[3] = s0.w; r.sn[4] = s1.x; r.sn[5] = s1.y; r.sn[6] = s1.z; r.sn[7] = s1.w;
; }
; __global__ void __launch_bounds__(512) hymba_fwd(Args a) {
;     ...
;                 { PrepIn cur; int u = wb; moba_prep_load(a, tid, u < 512 ? u : 0, cur);
;                   for (; u < 512; u += WG) { PrepIn nxt; moba_prep_unit(a, l, lds, tid, u, cur, nxt, (u + WG < 512) ? u + WG : u); cur = nxt; } }
.LBB0_424:
	s_or_b64 exec, exec, s[14:15]
	v_readlane_b32 s4, v245, 32
	v_readlane_b32 s5, v245, 33
	s_andn2_b64 vcc, exec, s[4:5]
	v_lshlrev_b32_e32 v124, 5, v96
	v_ashrrev_i32_e32 v97, 31, v96
	s_waitcnt lgkmcnt(0)
	s_barrier
	s_cbranch_vccnz .LBB0_435
	v_ashrrev_i32_e32 v98, 1, v96
	v_lshlrev_b32_e32 v196, 6, v96
	v_add_u32_e32 v196, 0x11000, v196
	v_and_b32_e32 v199, 63, v96
	v_lshrrev_b32_e32 v198, 6, v96
	v_lshlrev_b32_e32 v197, 4, v199
	v_lshl_or_b32 v197, v198, 12, v197
	v_add_u32_e32 v197, 0x11000, v197
	v_lshrrev_b32_e32 v201, 3, v199
	v_and_b32_e32 v200, 7, v199
	v_lshlrev_b32_e32 v200, 4, v200
	v_lshl_or_b32 v200, v201, 13, v200
	v_lshlrev_b32_e32 v199, 4, v199
	v_add_u32_e32 v201, 0x10000, v200
	v_add_u32_e32 v202, 0x20000, v200
	v_add_u32_e32 v203, 0x30000, v200
	v_readlane_b32 s4, v244, 8
	v_ashrrev_i32_e32 v99, 31, v98
	v_readlane_b32 s5, v244, 9
	v_and_b32_e32 v0, 32, v124
	v_lshlrev_b32_e32 v144, 1, v0
	v_lshl_add_u64 v[2:3], v[98:99], 0, s[4:5]
	v_readlane_b32 s4, v245, 34
	v_readlane_b32 s5, v245, 35
	v_and_b32_e32 v1, 1, v96
	v_lshlrev_b32_e32 v100, 5, v1
	v_lshl_add_u64 v[4:5], v[2:3], 0, s[4:5]
	v_readlane_b32 s4, v245, 40
	v_lshlrev_b64 v[6:7], 6, v[4:5]
	v_readlane_b32 s5, v245, 41
	v_lshlrev_b64 v[2:3], 7, v[2:3]
	v_cmp_eq_u32_e64 s[44:45], 0, v1
	v_lshl_add_u64 v[6:7], s[4:5], 0, v[6:7]
	v_readlane_b32 s4, v245, 38
	v_readlane_b32 s5, v245, 39
	global_load_dwordx4 v[48:51], v[6:7], off offset:48
	global_load_dwordx4 v[52:55], v[6:7], off offset:16
	global_load_dwordx4 v[56:59], v[6:7], off
	global_load_dwordx4 v[60:63], v[6:7], off offset:32
	v_lshl_add_u64 v[2:3], s[4:5], 0, v[2:3]
	v_lshl_add_u64 v[2:3], v[2:3], 0, v[144:145]
	v_readlane_b32 s4, v245, 36
	global_load_dwordx4 v[64:67], v[2:3], off offset:48
	global_load_dwordx4 v[68:71], v[2:3], off offset:32
	global_load_dwordx4 v[72:75], v[2:3], off offset:16
	global_load_dwordx4 v[76:79], v[2:3], off
	v_lshlrev_b64 v[2:3], 13, v[4:5]
	v_readlane_b32 s5, v245, 37
	v_lshrrev_b32_e32 v4, 5, v98
	v_cmp_gt_i32_e64 s[46:47], 64, v96
	v_lshl_add_u64 v[2:3], s[4:5], 0, v[2:3]
	v_lshl_add_u64 v[2:3], v[2:3], 0, v[144:145]
	global_load_dwordx4 v[80:83], v[2:3], off offset:48
	global_load_dwordx4 v[84:87], v[2:3], off offset:32
	global_load_dwordx4 v[88:91], v[2:3], off offset:16
	global_load_dwordx4 v[92:95], v[2:3], off
	s_add_i32 s4, 0, 0x10c00
	v_lshlrev_b32_e32 v2, 7, v1
	v_add_u32_e32 v125, s4, v2
	s_movk_i32 s4, 0x104
	v_add_u32_e32 v1, 0, v2
	v_mul_lo_u32 v2, v98, s4
	v_readlane_b32 s4, v244, 50
	v_and_b32_e32 v3, 63, v96
	v_lshlrev_b32_e32 v3, 2, v3
	v_lshl_add_u32 v126, v96, 2, s4
	s_movk_i32 s4, 0x2080
	v_mul_lo_u32 v4, v4, s4
	v_add3_u32 v127, v4, v3, 0
	v_lshlrev_b32_e32 v102, 1, v0
	v_add_u32_e32 v128, v1, v2
	v_readlane_b32 s5, v245, 44
	s_waitcnt vmcnt(11)
	v_mov_b32_e32 v105, v51
	s_waitcnt vmcnt(10)
	v_mov_b32_e32 v104, v55
	s_branch .LBB0_427

; #define LAS __attribute__((address_space(3)))
; __device__ __forceinline__ unsigned pk2(float lo, float hi) { f32x2_t v = {lo, hi}; bf16x2_t b = __builtin_convertvector(v, bf16x2_t); return __builtin_bit_cast(unsigned, b); }
; __device__ __forceinline__ float frsq(float x) { return __builtin_amdgcn_rsqf(x); }
; __device__ __forceinline__ void moba_prep_unit(const Args& a, int l, LAS unsigned char* lds, int tid, int u, const PrepIn& in, PrepIn& nxt, int unext) {
;     ...
;     for (int which = 0; which < 2; ++which) {
;         bf16_t* p = which ? (bf16_t*)(a.ws + WS_KC) + ((size_t)(b * 8 + h) * SEQ + j * 256 + tok) * 64 + half * 32 : proj + row * NCOL + CQA + h * 64 + half * 32;
;         const LAS float* g = (const LAS float*)(lds + 68608) + which * 64 + half * 32;
;         float v[32]; float ss = 0.f;
; #pragma unroll
;         for (int i = 0; i < 32; ++i) { v[i] = which ? vk[i] : vq[i]; ss += v[i] * v[i]; }
;         ss += __shfl_xor(ss, 1);
;         const float r = frsq(ss * (1.f / 64.f) + EPS) * (which ? 1.f : 0.125f * LOG2E);
; #pragma unroll
;         for (int c = 0; c < 8; ++c) { const f32x4 gg = *(const LAS f32x4*)(g + c * 4); v[c * 4] *= r * gg.x; v[c * 4 + 1] *= r * gg.y; v[c * 4 + 2] *= r * gg.z; v[c * 4 + 3] *= r * gg.w; }
;         if (half == 0) {
; #pragma unroll
;             for (int i = 0; i < 8; ++i) { const float x1 = v[i], x2 = v[8 + i]; v[i] = x1 * cs[i] - x2 * sn[i]; v[8 + i] = x2 * cs[i] + x1 * sn[i]; }
;         }
; #pragma unroll
;         for (int c = 0; c < 4; ++c) { u32x4 uu; uu.x = pk2(v[c * 8 + 0], v[c * 8 + 1]); uu.y = pk2(v[c * 8 + 2], v[c * 8 + 3]); uu.z = pk2(v[c * 8 + 4], v[c * 8 + 5]); uu.w = pk2(v[c * 8 + 6], v[c * 8 + 7]);
;             *(u32x4*)(p + c * 8) = uu; }
.LBB0_429:
	s_or_b64 exec, exec, s[14:15]
	s_ashr_i32 s14, s5, 6
	s_bfe_u32 s6, s5, 0x30003
	s_ashr_i32 s15, s14, 31
	s_lshl_b32 s6, s6, 8
	s_and_b32 s5, s5, 7
	s_lshl_b64 s[8:9], s[14:15], 24
	v_lshlrev_b32_e32 v157, 16, v68
	v_and_b32_e32 v158, 0xffff0000, v68
	v_lshlrev_b32_e32 v159, 16, v69
	v_and_b32_e32 v160, 0xffff0000, v69
	v_pk_mov_b32 v[68:69], v[70:71], v[64:65] op_sel:[1,0]
	v_lshlrev_b32_e32 v165, 16, v64
	v_and_b32_e32 v166, 0xffff0000, v64
	v_and_b32_e32 v168, 0xffff0000, v65
	v_lshlrev_b32_e32 v169, 16, v65
	v_lshl_add_u64 v[64:65], s[6:7], 0, v[98:99]
	s_add_u32 s8, s84, s8
	v_and_b32_e32 v170, 0xffff0000, v66
	v_lshlrev_b32_e32 v171, 16, v66
	v_and_b32_e32 v172, 0xffff0000, v67
	v_lshlrev_b32_e32 v173, 16, v67
	v_lshlrev_b64 v[66:67], 13, v[64:65]
	s_addc_u32 s9, s85, s9
	v_lshl_add_u64 v[66:67], s[8:9], 0, v[66:67]
	s_lshl_b32 s8, s5, 7
	s_mov_b32 s9, s7
	v_lshl_add_u64 v[66:67], v[66:67], 0, s[8:9]
	v_lshlrev_b32_e32 v144, 1, v100
	v_lshlrev_b32_e32 v51, 16, v79
	v_lshlrev_b32_e32 v138, 16, v78
	v_and_b32_e32 v139, 0xffff0000, v78
	v_and_b32_e32 v143, 0xffff0000, v79
	v_and_b32_e32 v164, 0xffff0000, v68
	v_lshl_add_u64 v[78:79], v[66:67], 0, v[144:145]
	v_cvt_pk_bf16_f32 v66, v122, v123
	v_cvt_pk_bf16_f32 v67, v120, v121
	v_cvt_pk_bf16_f32 v68, v118, v119
	v_cvt_pk_bf16_f32 v69, v112, v115
	ds_write_b128 v196, v[66:69]
	v_lshlrev_b32_e32 v130, 16, v76
	v_and_b32_e32 v131, 0xffff0000, v76
	v_cvt_pk_bf16_f32 v66, v94, v95
	v_cvt_pk_bf16_f32 v67, v108, v109
	v_cvt_pk_bf16_f32 v68, v110, v111
	v_cvt_pk_bf16_f32 v69, v88, v114
	ds_write_b128 v196, v[66:69] offset:16
	v_lshlrev_b32_e32 v134, 16, v77
	v_and_b32_e32 v135, 0xffff0000, v77
	v_cvt_pk_bf16_f32 v66, v89, v90
	v_cvt_pk_bf16_f32 v67, v91, v92
	v_cvt_pk_bf16_f32 v68, v93, v106
	v_cvt_pk_bf16_f32 v69, v107, v80
	ds_write_b128 v196, v[66:69] offset:32
	v_lshlrev_b32_e32 v161, 16, v70
	v_and_b32_e32 v162, 0xffff0000, v70
	v_pk_mul_f32 v[66:67], v[130:131], v[130:131]
	v_pk_mul_f32 v[68:69], v[134:135], v[134:135]
	v_add_f32_e32 v55, v66, v67
	v_add_f32_e32 v55, v68, v55
	v_lshlrev_b32_e32 v163, 16, v71
	v_pk_mul_f32 v[70:71], v[138:139], v[138:139]
	v_add_f32_e32 v55, v69, v55
	v_add_f32_e32 v55, v70, v55
	v_and_b32_e32 v142, 0xffff0000, v75
	v_add_f32_e32 v55, v71, v55
	v_lshlrev_b32_e32 v132, 16, v72
	v_and_b32_e32 v133, 0xffff0000, v72
	v_fmac_f32_e32 v55, v51, v51
	v_pk_mul_f32 v[66:67], v[142:143], v[142:143]
	v_pk_mul_f32 v[68:69], v[132:133], v[132:133]
	v_add_f32_e32 v55, v67, v55
	v_lshlrev_b32_e32 v136, 16, v73
	v_and_b32_e32 v137, 0xffff0000, v73
	v_add_f32_e32 v55, v68, v55
	v_add_f32_e32 v55, v69, v55
	v_pk_mul_f32 v[68:69], v[136:137], v[136:137]
	v_lshlrev_b32_e32 v140, 16, v74
	v_and_b32_e32 v141, 0xffff0000, v74
	v_add_f32_e32 v55, v68, v55
	v_add_f32_e32 v55, v69, v55
	v_pk_mul_f32 v[68:69], v[140:141], v[140:141]
	v_lshlrev_b32_e32 v156, 16, v75
	v_add_f32_e32 v55, v68, v55
	v_add_f32_e32 v55, v69, v55
	v_pk_mul_f32 v[68:69], v[156:157], v[156:157]
	v_mov_b32_e32 v167, v165
	v_add_f32_e32 v55, v68, v55
	v_add_f32_e32 v55, v66, v55
	v_add_f32_e32 v55, v69, v55
	v_pk_mul_f32 v[66:67], v[158:159], v[158:159]
	v_cvt_pk_bf16_f32 v68, v85, v86
	v_add_f32_e32 v55, v66, v55
	v_add_f32_e32 v55, v67, v55
	v_pk_mul_f32 v[66:67], v[160:161], v[160:161]
	v_cvt_pk_bf16_f32 v69, v87, v116
	v_add_f32_e32 v55, v66, v55
	v_add_f32_e32 v55, v67, v55
	v_pk_mul_f32 v[66:67], v[162:163], v[162:163]
	s_nop 0
	v_add_f32_e32 v55, v66, v55
	v_add_f32_e32 v55, v67, v55
	v_fmac_f32_e32 v55, v164, v164
	v_pk_mul_f32 v[66:67], v[166:167], v[166:167]
	v_mov_b32_e32 v167, v169
	v_add_f32_e32 v55, v67, v55
	v_add_f32_e32 v55, v66, v55
	v_pk_mul_f32 v[66:67], v[168:169], v[168:169]
	v_mov_b32_e32 v169, v171
	v_add_f32_e32 v55, v67, v55
	v_add_f32_e32 v55, v66, v55
	v_pk_mul_f32 v[66:67], v[170:171], v[170:171]
	v_mov_b32_e32 v171, v173
	v_add_f32_e32 v55, v67, v55
	v_add_f32_e32 v55, v66, v55
	v_pk_mul_f32 v[66:67], v[172:173], v[172:173]
	s_nop 0
	v_add_f32_e32 v55, v67, v55
	v_add_f32_e32 v55, v66, v55
	ds_bpermute_b32 v70, v103, v55
	v_cvt_pk_bf16_f32 v66, v81, v82
	v_cvt_pk_bf16_f32 v67, v83, v84
	s_waitcnt lgkmcnt(0)
	v_add_f32_e32 v55, v55, v70
	v_fmamk_f32 v55, v55, 0x3c800000, v186
	ds_read_b128 v[70:73], v125 offset:256
	ds_read_b128 v[74:77], v125 offset:272
	v_rsq_f32_e32 v118, v55
	ds_write_b128 v196, v[66:69] offset:48
	v_readfirstlane_b32 s18, v78
	v_readfirstlane_b32 s19, v79
	s_waitcnt lgkmcnt(0)
	ds_read_b128 v[204:207], v197
	ds_read_b128 v[208:211], v197 offset:1024
	ds_read_b128 v[212:215], v197 offset:2048
	ds_read_b128 v[216:219], v197 offset:3072
	s_waitcnt lgkmcnt(0)
	global_store_dwordx4 v200, v[204:207], s[18:19]
	global_store_dwordx4 v201, v[208:211], s[18:19]
	global_store_dwordx4 v202, v[212:215], s[18:19]
	global_store_dwordx4 v203, v[216:219], s[18:19]
	ds_read_b128 v[78:81], v125 offset:288
	ds_read_b128 v[84:87], v125 offset:304
	ds_read_b128 v[106:109], v125 offset:336
	s_waitcnt lgkmcnt(4)
	v_pk_mul_f32 v[68:69], v[70:71], v[118:119] op_sel_hi:[1,0]
	v_pk_mul_f32 v[70:71], v[72:73], v[118:119] op_sel_hi:[1,0]
	v_pk_mul_f32 v[82:83], v[68:69], v[130:131]
	s_waitcnt lgkmcnt(2)
	v_pk_mul_f32 v[68:69], v[78:79], v[118:119] op_sel_hi:[1,0]
	v_pk_mul_f32 v[88:89], v[70:71], v[134:135]
	v_pk_mul_f32 v[70:71], v[80:81], v[118:119] op_sel_hi:[1,0]
	ds_read_b128 v[78:81], v125 offset:320
	ds_read_b128 v[110:113], v125 offset:352
	ds_read_b128 v[114:117], v125 offset:368
	v_mul_f32_e32 v55, v76, v118
	s_waitcnt lgkmcnt(4)
; #define LAS __attribute__((address_space(3)))
; __device__ __forceinline__ unsigned pk2(float lo, float hi) { f32x2_t v = {lo, hi}; bf16x2_t b = __builtin_convertvector(v, bf16x2_t); return __builtin_bit_cast(unsigned, b); }
; __device__ __forceinline__ float frsq(float x) { return __builtin_amdgcn_rsqf(x); }
; #define BAR_LDS() do { asm volatile("s_waitcnt lgkmcnt(0)" ::: "memory"); __builtin_amdgcn_s_barrier(); asm volatile("" ::: "memory"); } while (0)
; __device__ __forceinline__ void moba_prep_unit(const Args& a, int l, LAS unsigned char* lds, int tid, int u, const PrepIn& in, PrepIn& nxt, int unext) {
;     ...
;     for (int which = 0; which < 2; ++which) {
;         bf16_t* p = which ? (bf16_t*)(a.ws + WS_KC) + ((size_t)(b * 8 + h) * SEQ + j * 256 + tok) * 64 + half * 32 : proj + row * NCOL + CQA + h * 64 + half * 32;
;         const LAS float* g = (const LAS float*)(lds + 68608) + which * 64 + half * 32;
;         float v[32]; float ss = 0.f;
; #pragma unroll
;         for (int i = 0; i < 32; ++i) { v[i] = which ? vk[i] : vq[i]; ss += v[i] * v[i]; }
;         ss += __shfl_xor(ss, 1);
;         const float r = frsq(ss * (1.f / 64.f) + EPS) * (which ? 1.f : 0.125f * LOG2E);
; #pragma unroll
;         for (int c = 0; c < 8; ++c) { const f32x4 gg = *(const LAS f32x4*)(g + c * 4); v[c * 4] *= r * gg.x; v[c * 4 + 1] *= r * gg.y; v[c * 4 + 2] *= r * gg.z; v[c * 4 + 3] *= r * gg.w; }
;         if (half == 0) {
; #pragma unroll
;             for (int i = 0; i < 8; ++i) { const float x1 = v[i], x2 = v[8 + i]; v[i] = x1 * cs[i] - x2 * sn[i]; v[8 + i] = x2 * cs[i] + x1 * sn[i]; }
;         }
; #pragma unroll
;         for (int c = 0; c < 4; ++c) { u32x4 uu; uu.x = pk2(v[c * 8 + 0], v[c * 8 + 1]); uu.y = pk2(v[c * 8 + 2], v[c * 8 + 3]); uu.z = pk2(v[c * 8 + 4], v[c * 8 + 5]); uu.w = pk2(v[c * 8 + 6], v[c * 8 + 7]);
;             *(u32x4*)(p + c * 8) = uu; }
;         if (which == 1) {
; #pragma unroll
;             for (int i = 0; i < 32; ++i) kt[tok * 65 + half * 32 + i] = v[i];
;         }
;     }
;     BAR_LDS();
	v_mov_b32_e32 v76, v87
	v_pk_mul_f32 v[72:73], v[74:75], v[118:119] op_sel_hi:[1,0]
	v_pk_mul_f32 v[74:75], v[118:119], v[76:77] op_sel_hi:[0,1]
	s_waitcnt lgkmcnt(2)
	v_mov_b32_e32 v87, v78
	v_pk_mul_f32 v[92:93], v[72:73], v[138:139]
	v_pk_mul_f32 v[72:73], v[118:119], v[84:85] op_sel_hi:[0,1]
	v_pk_mul_f32 v[84:85], v[74:75], v[142:143]
	v_pk_mul_f32 v[74:75], v[118:119], v[86:87] op_sel_hi:[0,1]
	v_mov_b32_e32 v76, v79
	v_mov_b32_e32 v77, v80
	v_pk_mov_b32 v[78:79], v[80:81], v[106:107] op_sel:[1,0]
	v_mov_b32_e32 v80, v107
	v_mov_b32_e32 v81, v108
	s_waitcnt lgkmcnt(1)
	v_pk_mov_b32 v[86:87], v[108:109], v[110:111] op_sel:[1,0]
	v_mov_b32_e32 v90, v111
	v_mov_b32_e32 v91, v112
	s_waitcnt lgkmcnt(0)
	v_pk_mov_b32 v[94:95], v[112:113], v[114:115] op_sel:[1,0]
	v_mov_b32_e32 v106, v115
	v_mov_b32_e32 v107, v116
	v_mul_f32_e32 v66, v55, v51
	v_pk_mul_f32 v[76:77], v[118:119], v[76:77] op_sel_hi:[0,1]
	v_pk_mul_f32 v[78:79], v[118:119], v[78:79] op_sel_hi:[0,1]
	v_pk_mul_f32 v[80:81], v[118:119], v[80:81] op_sel_hi:[0,1]
	v_pk_mul_f32 v[86:87], v[118:119], v[86:87] op_sel_hi:[0,1]
	v_pk_mul_f32 v[90:91], v[118:119], v[90:91] op_sel_hi:[0,1]
	v_pk_mul_f32 v[94:95], v[118:119], v[94:95] op_sel_hi:[0,1]
	v_pk_mul_f32 v[106:107], v[118:119], v[106:107] op_sel_hi:[0,1]
	v_mul_f32_e32 v51, v118, v117
	v_pk_mul_f32 v[68:69], v[68:69], v[132:133]
	v_pk_mul_f32 v[70:71], v[70:71], v[136:137]
	v_pk_mul_f32 v[72:73], v[72:73], v[140:141]
	v_pk_mul_f32 v[74:75], v[74:75], v[156:157]
	v_pk_mul_f32 v[76:77], v[76:77], v[158:159]
	v_pk_mul_f32 v[78:79], v[78:79], v[160:161]
	v_pk_mul_f32 v[80:81], v[80:81], v[162:163]
	v_pk_mul_f32 v[86:87], v[86:87], v[164:165]
	v_pk_mul_f32 v[90:91], v[90:91], v[166:167]
	v_pk_mul_f32 v[94:95], v[94:95], v[168:169]
	v_pk_mul_f32 v[106:107], v[106:107], v[170:171]
	v_mul_f32_e32 v103, v51, v172
	s_and_saveexec_b64 s[16:17], s[44:45]
	s_cbranch_execz .LBB0_431
	v_pk_mul_f32 v[108:109], v[60:61], v[68:69]
	v_pk_mul_f32 v[60:61], v[60:61], v[82:83]
	v_pk_fma_f32 v[108:109], v[56:57], v[82:83], v[108:109] neg_lo:[0,0,1] neg_hi:[0,0,1]
	v_pk_fma_f32 v[68:69], v[56:57], v[68:69], v[60:61]
	v_pk_mul_f32 v[56:57], v[62:63], v[70:71]
	v_pk_mul_f32 v[60:61], v[62:63], v[88:89]
	v_pk_fma_f32 v[56:57], v[58:59], v[88:89], v[56:57] neg_lo:[0,0,1] neg_hi:[0,0,1]
	v_pk_fma_f32 v[70:71], v[58:59], v[70:71], v[60:61]
	v_pk_mul_f32 v[58:59], v[48:49], v[72:73]
	v_pk_mul_f32 v[48:49], v[48:49], v[92:93]
	v_mov_b32_e32 v51, v105
	v_mov_b32_e32 v60, v74
	v_mov_b32_e32 v61, v84
	v_pk_fma_f32 v[58:59], v[52:53], v[92:93], v[58:59] neg_lo:[0,0,1] neg_hi:[0,0,1]
	v_pk_fma_f32 v[72:73], v[52:53], v[72:73], v[48:49]
	v_mul_f32_e32 v52, v50, v66
	v_mov_b32_e32 v55, v104
	v_mov_b32_e32 v67, v85
	v_pk_mul_f32 v[50:51], v[50:51], v[60:61]
	v_mul_f32_e32 v48, v54, v74
	v_pk_fma_f32 v[66:67], v[54:55], v[66:67], v[50:51] neg_lo:[0,0,1] neg_hi:[0,0,1]
	v_pk_mul_f32 v[50:51], v[104:105], v[84:85]
	v_mov_b32_e32 v82, v108
	v_mov_b32_e32 v49, v50
	v_mov_b32_e32 v53, v51
	v_pk_add_f32 v[48:49], v[48:49], v[52:53]
	v_mov_b32_e32 v83, v109
	v_mov_b32_e32 v88, v56
	v_mov_b32_e32 v89, v57
	v_mov_b32_e32 v92, v58
	v_mov_b32_e32 v93, v59
	v_mov_b32_e32 v85, v67
	v_mov_b32_e32 v74, v48
	v_mov_b32_e32 v84, v49
.LBB0_431:
	s_or_b64 exec, exec, s[16:17]
	s_lshl_b32 s8, s14, 3
	s_or_b32 s14, s8, s5
	s_ashr_i32 s15, s14, 31
	s_lshl_b64 s[8:9], s[14:15], 18
	s_add_u32 s8, s33, s8
	v_lshlrev_b64 v[48:49], 7, v[64:65]
	s_addc_u32 s9, s20, s9
	v_lshl_add_u64 v[48:49], s[8:9], 0, v[48:49]
	v_lshl_add_u64 v[52:53], v[48:49], 0, v[144:145]
	v_cvt_pk_bf16_f32 v48, v82, v83
	v_cvt_pk_bf16_f32 v49, v88, v89
	v_cvt_pk_bf16_f32 v50, v92, v93
	v_cvt_pk_bf16_f32 v51, v66, v85
	ds_write_b128 v196, v[48:51]
	s_mov_b32 s5, 0
	s_nop 0
	v_cvt_pk_bf16_f32 v48, v68, v69
	v_cvt_pk_bf16_f32 v49, v70, v71
	v_cvt_pk_bf16_f32 v50, v72, v73
	v_cvt_pk_bf16_f32 v51, v74, v84
	ds_write_b128 v196, v[48:51] offset:16
	s_nop 1
	v_cvt_pk_bf16_f32 v48, v75, v76
	v_cvt_pk_bf16_f32 v49, v77, v78
	v_cvt_pk_bf16_f32 v50, v79, v80
	v_cvt_pk_bf16_f32 v51, v81, v86
	ds_write_b128 v196, v[48:51] offset:32
	s_nop 1
	v_cvt_pk_bf16_f32 v48, v87, v90
	v_cvt_pk_bf16_f32 v49, v91, v94
	v_cvt_pk_bf16_f32 v50, v95, v106
	v_cvt_pk_bf16_f32 v51, v107, v103
	ds_write_b128 v196, v[48:51] offset:48
	v_readfirstlane_b32 s18, v52
	v_readfirstlane_b32 s19, v53
	s_waitcnt lgkmcnt(0)
	ds_read_b128 v[204:207], v197
	ds_read_b128 v[208:211], v197 offset:1024
	ds_read_b128 v[212:215], v197 offset:2048
	ds_read_b128 v[216:219], v197 offset:3072
	s_waitcnt lgkmcnt(0)
	global_store_dwordx4 v199, v[204:207], s[18:19]
	global_store_dwordx4 v199, v[208:211], s[18:19] offset:1024
	global_store_dwordx4 v199, v[212:215], s[18:19] offset:2048
	global_store_dwordx4 v199, v[216:219], s[18:19] offset:3072
	ds_write2_b32 v128, v82, v83 offset1:1
	ds_write2_b32 v128, v88, v89 offset0:2 offset1:3
	ds_write2_b32 v128, v92, v93 offset0:4 offset1:5
	ds_write2_b32 v128, v66, v85 offset0:6 offset1:7
	ds_write2_b32 v128, v68, v69 offset0:8 offset1:9
	ds_write2_b32 v128, v70, v71 offset0:10 offset1:11
	ds_write2_b32 v128, v72, v73 offset0:12 offset1:13
	ds_write2_b32 v128, v74, v84 offset0:14 offset1:15
	ds_write2_b32 v128, v75, v76 offset0:16 offset1:17
	ds_write2_b32 v128, v77, v78 offset0:18 offset1:19
	ds_write2_b32 v128, v79, v80 offset0:20 offset1:21
	ds_write2_b32 v128, v81, v86 offset0:22 offset1:23
	ds_write2_b32 v128, v87, v90 offset0:24 offset1:25
	ds_write2_b32 v128, v91, v94 offset0:26 offset1:27
	ds_write2_b32 v128, v95, v106 offset0:28 offset1:29
	ds_write2_b32 v128, v107, v103 offset0:30 offset1:31
	s_waitcnt lgkmcnt(0)
	s_barrier
	v_mov_b32_e32 v48, 0
